# swiglu epilogue stores: SGPR base + 32-bit row*stride offset (v_mul_u32_u24 + add) instead of 64-bit v_mad_i64_i32 + 64-bit add per row
# speedup vs baseline: 1.0055x; 1.0055x over previous
.LBB0_402:
	s_add_u32 s20, s18, 0xfffc0080
	s_addc_u32 s21, s19, -1
	s_add_i32 s41, 0, 0x10000
	ds_read_b128 v[138:141], v218
	ds_read_b128 v[148:151], v218 offset:1024
	ds_read_b128 v[152:155], v218 offset:2048
	ds_read_b128 v[156:159], v218 offset:3072
	s_cmp_eq_u32 s40, 12
	s_cselect_b32 s23, s1, s21
	s_cselect_b32 s22, s9, s20
	s_cselect_b32 s21, s11, s39
	s_cselect_b32 s20, s33, s38
	s_add_i32 m0, s17, 0xc000
	ds_read_b128 v[160:163], v146
	ds_read_b128 v[164:167], v146 offset:1024
	ds_read_b128 v[168:171], v146 offset:2048
	ds_read_b128 v[172:175], v146 offset:3072
	ds_read_b128 v[176:179], v146 offset:4096
	ds_read_b128 v[180:183], v146 offset:5120
	ds_read_b128 v[184:187], v146 offset:6144
	ds_read_b128 v[188:191], v146 offset:7168
	global_load_lds_dwordx4 v136, s[18:19]
	s_add_i32 m0, s17, 0xe000
	s_nop 0
	global_load_lds_dwordx4 v134, s[18:19]
	s_waitcnt lgkmcnt(8)
	s_barrier
	s_waitcnt lgkmcnt(0)
	v_mfma_f32_16x16x32_bf16 v[124:127], v[138:141], v[160:163], v[124:127]
	v_mfma_f32_16x16x32_bf16 v[116:119], v[152:155], v[160:163], v[116:119]
	v_mfma_f32_16x16x32_bf16 v[108:111], v[138:141], v[168:171], v[108:111]
	v_mfma_f32_16x16x32_bf16 v[100:103], v[152:155], v[168:171], v[100:103]
	v_mfma_f32_16x16x32_bf16 v[92:95], v[138:141], v[176:179], v[92:95]
	v_mfma_f32_16x16x32_bf16 v[84:87], v[152:155], v[176:179], v[84:87]
	v_mfma_f32_16x16x32_bf16 v[76:79], v[138:141], v[184:187], v[76:79]
	v_mfma_f32_16x16x32_bf16 v[68:71], v[152:155], v[184:187], v[68:71]
	v_mfma_f32_16x16x32_bf16 v[124:127], v[148:151], v[164:167], v[124:127]
	v_mfma_f32_16x16x32_bf16 v[116:119], v[156:159], v[164:167], v[116:119]
	v_mfma_f32_16x16x32_bf16 v[108:111], v[148:151], v[172:175], v[108:111]
	v_mfma_f32_16x16x32_bf16 v[100:103], v[156:159], v[172:175], v[100:103]
	v_mfma_f32_16x16x32_bf16 v[92:95], v[148:151], v[180:183], v[92:95]
	v_mfma_f32_16x16x32_bf16 v[84:87], v[156:159], v[180:183], v[84:87]
	v_mfma_f32_16x16x32_bf16 v[76:79], v[148:151], v[188:191], v[76:79]
	v_mfma_f32_16x16x32_bf16 v[68:71], v[156:159], v[188:191], v[68:71]
	s_barrier
	s_add_i32 s44, 0, 0x14000
	s_add_i32 s41, s41, s28
	ds_read_b128 v[198:201], v219
	ds_read_b128 v[206:209], v219 offset:1024
	ds_read_b128 v[210:213], v219 offset:2048
	ds_read_b128 v[214:217], v219 offset:3072
	s_mov_b32 m0, s41
	s_nop 0
	global_load_lds_dwordx4 v192, s[20:21]
	s_add_i32 m0, s41, 0x2000
	s_nop 0
	global_load_lds_dwordx4 v128, s[20:21]
	s_barrier
	s_waitcnt lgkmcnt(0)
	v_mfma_f32_16x16x32_bf16 v[120:123], v[198:201], v[160:163], v[120:123]
	v_mfma_f32_16x16x32_bf16 v[112:115], v[210:213], v[160:163], v[112:115]
	v_mfma_f32_16x16x32_bf16 v[104:107], v[198:201], v[168:171], v[104:107]
	v_mfma_f32_16x16x32_bf16 v[96:99], v[210:213], v[168:171], v[96:99]
	v_mfma_f32_16x16x32_bf16 v[88:91], v[198:201], v[176:179], v[88:91]
	v_mfma_f32_16x16x32_bf16 v[80:83], v[210:213], v[176:179], v[80:83]
	v_mfma_f32_16x16x32_bf16 v[72:75], v[198:201], v[184:187], v[72:75]
	v_mfma_f32_16x16x32_bf16 v[64:67], v[210:213], v[184:187], v[64:67]
	v_mfma_f32_16x16x32_bf16 v[120:123], v[206:209], v[164:167], v[120:123]
	v_mfma_f32_16x16x32_bf16 v[112:115], v[214:217], v[164:167], v[112:115]
	v_mfma_f32_16x16x32_bf16 v[104:107], v[206:209], v[172:175], v[104:107]
	v_mfma_f32_16x16x32_bf16 v[96:99], v[214:217], v[172:175], v[96:99]
	v_mfma_f32_16x16x32_bf16 v[88:91], v[206:209], v[180:183], v[88:91]
	v_mfma_f32_16x16x32_bf16 v[80:83], v[214:217], v[180:183], v[80:83]
	v_mfma_f32_16x16x32_bf16 v[72:75], v[206:209], v[188:191], v[72:75]
	v_mfma_f32_16x16x32_bf16 v[64:67], v[214:217], v[188:191], v[64:67]
	s_mov_b32 m0, s17
	s_add_u32 vcc_lo, s22, 0x80
	s_addc_u32 vcc_hi, s23, 0
	s_barrier
	ds_read_b128 v[160:163], v146 offset:16384
	ds_read_b128 v[164:167], v146 offset:17408
	ds_read_b128 v[168:171], v146 offset:18432
	ds_read_b128 v[172:175], v146 offset:19456
	ds_read_b128 v[176:179], v146 offset:20480
	ds_read_b128 v[180:183], v146 offset:21504
	ds_read_b128 v[184:187], v146 offset:22528
	ds_read_b128 v[188:191], v146 offset:23552
	global_load_lds_dwordx4 v132, s[22:23]
	s_mov_b32 m0, s29
	s_nop 0
	global_load_lds_dwordx4 v130, s[22:23]
	s_barrier
	s_waitcnt lgkmcnt(0)
	v_mfma_f32_16x16x32_bf16 v[60:63], v[138:141], v[160:163], v[60:63]
	v_mfma_f32_16x16x32_bf16 v[52:55], v[152:155], v[160:163], v[52:55]
	v_mfma_f32_16x16x32_bf16 v[44:47], v[138:141], v[168:171], v[44:47]
	v_mfma_f32_16x16x32_bf16 v[36:39], v[152:155], v[168:171], v[36:39]
	v_mfma_f32_16x16x32_bf16 v[28:31], v[138:141], v[176:179], v[28:31]
	v_mfma_f32_16x16x32_bf16 v[20:23], v[152:155], v[176:179], v[20:23]
	v_mfma_f32_16x16x32_bf16 v[12:15], v[138:141], v[184:187], v[12:15]
	v_mfma_f32_16x16x32_bf16 v[4:7], v[152:155], v[184:187], v[4:7]
	v_mfma_f32_16x16x32_bf16 v[60:63], v[148:151], v[164:167], v[60:63]
	v_mfma_f32_16x16x32_bf16 v[52:55], v[156:159], v[164:167], v[52:55]
	v_mfma_f32_16x16x32_bf16 v[44:47], v[148:151], v[172:175], v[44:47]
	v_mfma_f32_16x16x32_bf16 v[36:39], v[156:159], v[172:175], v[36:39]
	v_mfma_f32_16x16x32_bf16 v[28:31], v[148:151], v[180:183], v[28:31]
	v_mfma_f32_16x16x32_bf16 v[20:23], v[156:159], v[180:183], v[20:23]
	v_mfma_f32_16x16x32_bf16 v[12:15], v[148:151], v[188:191], v[12:15]
	v_mfma_f32_16x16x32_bf16 v[4:7], v[156:159], v[188:191], v[4:7]
	s_barrier
	s_add_u32 s42, s20, 0x40000
	s_addc_u32 s43, s21, 0
	s_add_i32 s41, s44, s28
	s_mov_b32 m0, s41
	s_nop 0
	global_load_lds_dwordx4 v192, s[42:43]
	s_add_i32 m0, s41, 0x2000
	s_nop 0
	global_load_lds_dwordx4 v128, s[42:43]
	s_waitcnt vmcnt(6)
	s_barrier
	v_mfma_f32_16x16x32_bf16 v[56:59], v[198:201], v[160:163], v[56:59]
	v_mfma_f32_16x16x32_bf16 v[48:51], v[210:213], v[160:163], v[48:51]
	v_mfma_f32_16x16x32_bf16 v[40:43], v[198:201], v[168:171], v[40:43]
	v_mfma_f32_16x16x32_bf16 v[32:35], v[210:213], v[168:171], v[32:35]
	v_mfma_f32_16x16x32_bf16 v[24:27], v[198:201], v[176:179], v[24:27]
	v_mfma_f32_16x16x32_bf16 v[16:19], v[210:213], v[176:179], v[16:19]
	v_mfma_f32_16x16x32_bf16 v[8:11], v[198:201], v[184:187], v[8:11]
	v_mfma_f32_16x16x32_bf16 v[0:3], v[210:213], v[184:187], v[0:3]
	v_mfma_f32_16x16x32_bf16 v[56:59], v[206:209], v[164:167], v[56:59]
	v_mfma_f32_16x16x32_bf16 v[48:51], v[214:217], v[164:167], v[48:51]
	v_mfma_f32_16x16x32_bf16 v[40:43], v[206:209], v[172:175], v[40:43]
	v_mfma_f32_16x16x32_bf16 v[32:35], v[214:217], v[172:175], v[32:35]
	v_mfma_f32_16x16x32_bf16 v[24:27], v[206:209], v[180:183], v[24:27]
	v_mfma_f32_16x16x32_bf16 v[16:19], v[214:217], v[180:183], v[16:19]
	v_mfma_f32_16x16x32_bf16 v[8:11], v[206:209], v[188:191], v[8:11]
	v_mfma_f32_16x16x32_bf16 v[0:3], v[214:217], v[188:191], v[0:3]
	s_add_i32 s41, 0, 0x18000
	s_barrier
	ds_read_b128 v[138:141], v220
	ds_read_b128 v[148:151], v220 offset:1024
	ds_read_b128 v[152:155], v220 offset:2048
	ds_read_b128 v[156:159], v220 offset:3072
	s_add_u32 s22, s22, 0x40000
	s_addc_u32 s23, s23, 0
	s_mov_b32 m0, s30
	ds_read_b128 v[160:163], v146 offset:32768
	ds_read_b128 v[164:167], v146 offset:33792
	ds_read_b128 v[168:171], v146 offset:34816
	ds_read_b128 v[172:175], v146 offset:35840
	ds_read_b128 v[176:179], v146 offset:36864
	ds_read_b128 v[180:183], v146 offset:37888
	ds_read_b128 v[184:187], v146 offset:38912
	ds_read_b128 v[188:191], v146 offset:39936
	global_load_lds_dwordx4 v132, s[22:23]
	s_mov_b32 m0, s31
	s_nop 0
	global_load_lds_dwordx4 v130, s[22:23]
	s_waitcnt lgkmcnt(8)
	s_barrier
	s_waitcnt lgkmcnt(0)
	v_mfma_f32_16x16x32_bf16 v[124:127], v[138:141], v[160:163], v[124:127]
	v_mfma_f32_16x16x32_bf16 v[116:119], v[152:155], v[160:163], v[116:119]
	v_mfma_f32_16x16x32_bf16 v[108:111], v[138:141], v[168:171], v[108:111]
	v_mfma_f32_16x16x32_bf16 v[100:103], v[152:155], v[168:171], v[100:103]
	v_mfma_f32_16x16x32_bf16 v[92:95], v[138:141], v[176:179], v[92:95]
	v_mfma_f32_16x16x32_bf16 v[84:87], v[152:155], v[176:179], v[84:87]
	v_mfma_f32_16x16x32_bf16 v[76:79], v[138:141], v[184:187], v[76:79]
	v_mfma_f32_16x16x32_bf16 v[68:71], v[152:155], v[184:187], v[68:71]
	v_mfma_f32_16x16x32_bf16 v[124:127], v[148:151], v[164:167], v[124:127]
	v_mfma_f32_16x16x32_bf16 v[116:119], v[156:159], v[164:167], v[116:119]
	v_mfma_f32_16x16x32_bf16 v[108:111], v[148:151], v[172:175], v[108:111]
	v_mfma_f32_16x16x32_bf16 v[100:103], v[156:159], v[172:175], v[100:103]
	v_mfma_f32_16x16x32_bf16 v[92:95], v[148:151], v[180:183], v[92:95]
	v_mfma_f32_16x16x32_bf16 v[84:87], v[156:159], v[180:183], v[84:87]
	v_mfma_f32_16x16x32_bf16 v[76:79], v[148:151], v[188:191], v[76:79]
	v_mfma_f32_16x16x32_bf16 v[68:71], v[156:159], v[188:191], v[68:71]
	s_barrier
	s_add_i32 s22, 0, 0x1c000
	s_add_i32 s23, s41, s28
	s_add_u32 s100, s20, 0x80
	s_addc_u32 s101, s21, 0
	s_mov_b32 m0, s23
	ds_read_b128 v[198:201], v221
	ds_read_b128 v[206:209], v221 offset:1024
	ds_read_b128 v[210:213], v221 offset:2048
	ds_read_b128 v[214:217], v221 offset:3072
	global_load_lds_dwordx4 v192, s[100:101]
	s_add_i32 m0, s23, 0x2000
	s_nop 0
	global_load_lds_dwordx4 v128, s[100:101]
	s_barrier
	s_waitcnt lgkmcnt(0)
	v_mfma_f32_16x16x32_bf16 v[120:123], v[198:201], v[160:163], v[120:123]
	v_mfma_f32_16x16x32_bf16 v[112:115], v[210:213], v[160:163], v[112:115]
	v_mfma_f32_16x16x32_bf16 v[104:107], v[198:201], v[168:171], v[104:107]
	v_mfma_f32_16x16x32_bf16 v[96:99], v[210:213], v[168:171], v[96:99]
	v_mfma_f32_16x16x32_bf16 v[88:91], v[198:201], v[176:179], v[88:91]
	v_mfma_f32_16x16x32_bf16 v[80:83], v[210:213], v[176:179], v[80:83]
	v_mfma_f32_16x16x32_bf16 v[72:75], v[198:201], v[184:187], v[72:75]
	v_mfma_f32_16x16x32_bf16 v[64:67], v[210:213], v[184:187], v[64:67]
	v_mfma_f32_16x16x32_bf16 v[120:123], v[206:209], v[164:167], v[120:123]
	v_mfma_f32_16x16x32_bf16 v[112:115], v[214:217], v[164:167], v[112:115]
	v_mfma_f32_16x16x32_bf16 v[104:107], v[206:209], v[172:175], v[104:107]
	v_mfma_f32_16x16x32_bf16 v[96:99], v[214:217], v[172:175], v[96:99]
	v_mfma_f32_16x16x32_bf16 v[88:91], v[206:209], v[180:183], v[88:91]
	v_mfma_f32_16x16x32_bf16 v[80:83], v[214:217], v[180:183], v[80:83]
	v_mfma_f32_16x16x32_bf16 v[72:75], v[206:209], v[188:191], v[72:75]
	v_mfma_f32_16x16x32_bf16 v[64:67], v[214:217], v[188:191], v[64:67]
	s_mov_b32 m0, s34
	s_barrier
	ds_read_b128 v[160:163], v146 offset:49152
	ds_read_b128 v[164:167], v146 offset:50176
	ds_read_b128 v[168:171], v146 offset:51200
	ds_read_b128 v[172:175], v146 offset:52224
	ds_read_b128 v[176:179], v146 offset:53248
	ds_read_b128 v[180:183], v146 offset:54272
	ds_read_b128 v[184:187], v146 offset:55296
	ds_read_b128 v[188:191], v146 offset:56320
	global_load_lds_dwordx4 v132, vcc
	s_mov_b32 m0, s35
	s_nop 0
	global_load_lds_dwordx4 v130, vcc
	s_barrier
	s_waitcnt lgkmcnt(0)
	v_mfma_f32_16x16x32_bf16 v[60:63], v[138:141], v[160:163], v[60:63]
	v_mfma_f32_16x16x32_bf16 v[52:55], v[152:155], v[160:163], v[52:55]
	v_mfma_f32_16x16x32_bf16 v[44:47], v[138:141], v[168:171], v[44:47]
	v_mfma_f32_16x16x32_bf16 v[36:39], v[152:155], v[168:171], v[36:39]
	v_mfma_f32_16x16x32_bf16 v[28:31], v[138:141], v[176:179], v[28:31]
	v_mfma_f32_16x16x32_bf16 v[20:23], v[152:155], v[176:179], v[20:23]
	v_mfma_f32_16x16x32_bf16 v[12:15], v[138:141], v[184:187], v[12:15]
	v_mfma_f32_16x16x32_bf16 v[4:7], v[152:155], v[184:187], v[4:7]
	v_mfma_f32_16x16x32_bf16 v[60:63], v[148:151], v[164:167], v[60:63]
	v_mfma_f32_16x16x32_bf16 v[52:55], v[156:159], v[164:167], v[52:55]
	v_mfma_f32_16x16x32_bf16 v[44:47], v[148:151], v[172:175], v[44:47]
	v_mfma_f32_16x16x32_bf16 v[36:39], v[156:159], v[172:175], v[36:39]
	v_mfma_f32_16x16x32_bf16 v[28:31], v[148:151], v[180:183], v[28:31]
	v_mfma_f32_16x16x32_bf16 v[20:23], v[156:159], v[180:183], v[20:23]
	v_mfma_f32_16x16x32_bf16 v[12:15], v[148:151], v[188:191], v[12:15]
	v_mfma_f32_16x16x32_bf16 v[4:7], v[156:159], v[188:191], v[4:7]
	s_barrier
	s_add_u32 s20, s20, 0x40080
	s_addc_u32 s21, s21, 0
	s_add_i32 s22, s22, s28
	s_mov_b32 m0, s22
	s_nop 0
	global_load_lds_dwordx4 v192, s[20:21]
	s_add_i32 m0, s22, 0x2000
	s_nop 0
	global_load_lds_dwordx4 v128, s[20:21]
	s_waitcnt vmcnt(6)
	s_barrier
	v_mfma_f32_16x16x32_bf16 v[56:59], v[198:201], v[160:163], v[56:59]
	v_mfma_f32_16x16x32_bf16 v[48:51], v[210:213], v[160:163], v[48:51]
	v_mfma_f32_16x16x32_bf16 v[40:43], v[198:201], v[168:171], v[40:43]
	v_mfma_f32_16x16x32_bf16 v[32:35], v[210:213], v[168:171], v[32:35]
	v_mfma_f32_16x16x32_bf16 v[24:27], v[198:201], v[176:179], v[24:27]
	v_mfma_f32_16x16x32_bf16 v[16:19], v[210:213], v[176:179], v[16:19]
	v_mfma_f32_16x16x32_bf16 v[8:11], v[198:201], v[184:187], v[8:11]
	v_mfma_f32_16x16x32_bf16 v[0:3], v[210:213], v[184:187], v[0:3]
	v_mfma_f32_16x16x32_bf16 v[56:59], v[206:209], v[164:167], v[56:59]
	v_mfma_f32_16x16x32_bf16 v[48:51], v[214:217], v[164:167], v[48:51]
	v_mfma_f32_16x16x32_bf16 v[40:43], v[206:209], v[172:175], v[40:43]
	v_mfma_f32_16x16x32_bf16 v[32:35], v[214:217], v[172:175], v[32:35]
	v_mfma_f32_16x16x32_bf16 v[24:27], v[206:209], v[180:183], v[24:27]
	v_mfma_f32_16x16x32_bf16 v[16:19], v[214:217], v[180:183], v[16:19]
	v_mfma_f32_16x16x32_bf16 v[8:11], v[206:209], v[188:191], v[8:11]
	v_mfma_f32_16x16x32_bf16 v[0:3], v[214:217], v[188:191], v[0:3]
	s_add_i32 s40, s40, 2
	s_add_u32 s38, s38, 0x100
	s_addc_u32 s39, s39, 0
	s_add_u32 s18, s18, 0x100
	s_addc_u32 s19, s19, 0
	s_cmp_gt_u32 s40, 13
	s_barrier
	s_cbranch_scc0 .LBB0_402
	v_mov_b32_e32 v139, v252
	s_lshl_b32 s9, s16, 8
	v_readfirstlane_b32 s1, v139
	s_ashr_i32 s11, s1, 2
	s_andn2_b32 s11, s11, 63
	s_lshr_b32 s1, s1, 1
	s_add_i32 s11, s11, s9
	s_lshl_b32 s0, s0, 7
	s_and_b32 s1, s1, 0x60
	v_and_or_b32 v138, v139, 15, s11
	s_or_b32 s0, s1, s0
	v_lshrrev_b32_e32 v139, 1, v139
	v_and_or_b32 v142, v139, 24, s0
	v_ashrrev_i32_e32 v139, 31, v138
	v_lshl_add_u64 v[140:141], v[138:139], 2, s[6:7]
	v_pk_mul_f32 v[120:121], v[124:125], v[120:121]
	v_pk_mul_f32 v[122:123], v[126:127], v[122:123]
	v_pk_mul_f32 v[112:113], v[116:117], v[112:113]
	v_pk_mul_f32 v[114:115], v[118:119], v[114:115]
	v_ashrrev_i32_e32 v143, 31, v142
	s_movk_i32 s9, 0x1600
	v_pk_mul_f32 v[104:105], v[108:109], v[104:105]
	v_pk_mul_f32 v[106:107], v[110:111], v[106:107]
	v_pk_mul_f32 v[96:97], v[100:101], v[96:97]
	v_or_b32_e32 v150, 16, v138
	v_pk_mul_f32 v[98:99], v[102:103], v[98:99]
	v_pk_mul_f32 v[88:89], v[92:93], v[88:89]
	v_pk_mul_f32 v[90:91], v[94:95], v[90:91]
	v_pk_mul_f32 v[80:81], v[84:85], v[80:81]
	v_or_b32_e32 v148, 32, v138
	v_pk_mul_f32 v[82:83], v[86:87], v[82:83]
	v_pk_mul_f32 v[72:73], v[76:77], v[72:73]
	v_pk_mul_f32 v[74:75], v[78:79], v[74:75]
	v_pk_mul_f32 v[64:65], v[68:69], v[64:65]
	v_or_b32_e32 v139, 48, v138
	v_pk_mul_f32 v[66:67], v[70:71], v[66:67]
	v_pk_mul_f32 v[56:57], v[60:61], v[56:57]
	v_pk_mul_f32 v[58:59], v[62:63], v[58:59]
	v_pk_mul_f32 v[48:49], v[52:53], v[48:49]
	v_pk_mul_f32 v[50:51], v[54:55], v[50:51]
	v_pk_mul_f32 v[40:41], v[44:45], v[40:41]
	v_pk_mul_f32 v[42:43], v[46:47], v[42:43]
	v_pk_mul_f32 v[32:33], v[36:37], v[32:33]
	v_pk_mul_f32 v[34:35], v[38:39], v[34:35]
	v_pk_mul_f32 v[24:25], v[28:29], v[24:25]
	v_pk_mul_f32 v[26:27], v[30:31], v[26:27]
	v_pk_mul_f32 v[16:17], v[20:21], v[16:17]
	v_pk_mul_f32 v[18:19], v[22:23], v[18:19]
	v_pk_mul_f32 v[8:9], v[12:13], v[8:9]
	v_pk_mul_f32 v[10:11], v[14:15], v[10:11]
	v_pk_mul_f32 v[0:1], v[4:5], v[0:1]
	v_pk_mul_f32 v[2:3], v[6:7], v[2:3]
	s_mov_b32 s16, s8
	s_mov_b64 s[18:19], s[14:15]
	s_mov_b64 s[20:21], s[12:13]
	v_fmamk_f32 v239, v231, 0x3a800000, v194
	s_nop 0
	v_rsq_f32_e32 v144, v239
	s_nop 0
	v_mul_f32_e32 v152, 0xbfb8aa3b, v144
	v_pk_mul_f32 v[156:157], v[124:125], v[152:153] op_sel_hi:[1,0]
	v_pk_mul_f32 v[154:155], v[126:127], v[152:153] op_sel_hi:[1,0]
	v_exp_f32_e32 v153, v156
	s_nop 0
	v_fma_f32 v153, v153, v239, v239
	v_rcp_f32_e32 v156, v153
	v_exp_f32_e32 v153, v157
	s_nop 0
	v_fma_f32 v153, v153, v239, v239
	v_rcp_f32_e32 v157, v153
	v_exp_f32_e32 v153, v154
	s_nop 0
	v_fma_f32 v153, v153, v239, v239
	v_rcp_f32_e32 v154, v153
	v_exp_f32_e32 v153, v155
	v_pk_mul_f32 v[120:121], v[120:121], v[156:157]
	v_fma_f32 v153, v153, v239, v239
	v_rcp_f32_e32 v155, v153
	v_cvt_pk_bf16_f32 v120, v120, v121
	v_readlane_b32 s0, v254, 29
	s_nop 0
	v_pk_mul_f32 v[122:123], v[122:123], v[154:155]
	v_readlane_b32 s1, v254, 30
	v_cvt_pk_bf16_f32 v121, v122, v123
	v_pk_mul_f32 v[124:125], v[116:117], v[152:153] op_sel_hi:[1,0]
	v_pk_mul_f32 v[122:123], v[118:119], v[152:153] op_sel_hi:[1,0]
	v_exp_f32_e32 v124, v124
	v_exp_f32_e32 v125, v125
	v_exp_f32_e32 v122, v122
	v_exp_f32_e32 v123, v123
	v_fma_f32 v124, v124, v239, v239
	v_fma_f32 v125, v125, v239, v239
	v_rcp_f32_e32 v124, v124
	v_rcp_f32_e32 v125, v125
	v_fma_f32 v122, v122, v239, v239
	v_fma_f32 v123, v123, v239, v239
	v_rcp_f32_e32 v122, v122
	v_rcp_f32_e32 v123, v123
	s_nop 0
	v_pk_mul_f32 v[112:113], v[112:113], v[124:125]
	s_nop 0
	v_pk_mul_f32 v[114:115], v[114:115], v[122:123]
	v_cvt_pk_bf16_f32 v122, v112, v113
	v_cvt_pk_bf16_f32 v123, v114, v115
	v_mul_u32_u24_e32 v116, 0x1600, v138
	v_lshlrev_b32_e32 v114, 1, v142
	v_add_u32_e32 v116, v116, v114
	global_store_dwordx4 v116, v[120:123], s[0:1]
	v_fmamk_f32 v239, v232, 0x3a800000, v194
	s_nop 0
	v_rsq_f32_e32 v116, v239
	s_nop 0
	v_mul_f32_e32 v118, 0xbfb8aa3b, v116
	v_pk_mul_f32 v[120:121], v[108:109], v[118:119] op_sel_hi:[1,0]
	v_pk_mul_f32 v[122:123], v[110:111], v[118:119] op_sel_hi:[1,0]
	v_exp_f32_e32 v117, v120
	s_nop 0
	v_fma_f32 v117, v117, v239, v239
	v_rcp_f32_e32 v120, v117
	v_exp_f32_e32 v117, v121
	s_nop 0
	v_fma_f32 v117, v117, v239, v239
	v_rcp_f32_e32 v121, v117
	v_exp_f32_e32 v117, v122
	s_nop 0
	v_fma_f32 v117, v117, v239, v239
	v_rcp_f32_e32 v122, v117
	v_exp_f32_e32 v117, v123
	s_nop 0
	v_fma_f32 v117, v117, v239, v239
	v_rcp_f32_e32 v123, v117
	s_nop 0
	v_pk_mul_f32 v[104:105], v[104:105], v[120:121]
	s_nop 0
	v_pk_mul_f32 v[106:107], v[106:107], v[122:123]
	v_cvt_pk_bf16_f32 v104, v104, v105
	v_cvt_pk_bf16_f32 v105, v106, v107
	v_pk_mul_f32 v[108:109], v[100:101], v[118:119] op_sel_hi:[1,0]
	v_pk_mul_f32 v[106:107], v[102:103], v[118:119] op_sel_hi:[1,0]
	v_exp_f32_e32 v108, v108
	v_exp_f32_e32 v109, v109
	v_exp_f32_e32 v106, v106
	v_exp_f32_e32 v107, v107
	v_fma_f32 v108, v108, v239, v239
	v_fma_f32 v109, v109, v239, v239
	v_rcp_f32_e32 v108, v108
	v_rcp_f32_e32 v109, v109
	v_fma_f32 v106, v106, v239, v239
	v_fma_f32 v107, v107, v239, v239
	v_rcp_f32_e32 v106, v106
	v_rcp_f32_e32 v107, v107
	s_nop 0
	v_pk_mul_f32 v[96:97], v[96:97], v[108:109]
	s_nop 0
	v_pk_mul_f32 v[98:99], v[98:99], v[106:107]
	v_cvt_pk_bf16_f32 v106, v96, v97
	v_mul_u32_u24_e32 v96, 0x1600, v150
	v_cvt_pk_bf16_f32 v107, v98, v99
	v_add_u32_e32 v96, v96, v114
	global_store_dwordx4 v96, v[104:107], s[0:1]
	v_fmamk_f32 v239, v233, 0x3a800000, v194
	s_nop 0
	v_rsq_f32_e32 v96, v239
	s_nop 0
	v_mov_b32_e32 v97, v96
	v_mul_f32_e32 v96, 0xbfb8aa3b, v97
	v_pk_mul_f32 v[102:103], v[92:93], v[96:97] op_sel_hi:[1,0]
	s_nop 0
	v_pk_mul_f32 v[100:101], v[94:95], v[96:97] op_sel_hi:[1,0]
	v_exp_f32_e32 v97, v102
	s_nop 0
	v_fma_f32 v97, v97, v239, v239
	v_rcp_f32_e32 v102, v97
	v_exp_f32_e32 v97, v103
	s_nop 0
	v_fma_f32 v97, v97, v239, v239
	v_rcp_f32_e32 v103, v97
	v_exp_f32_e32 v97, v100
	s_nop 0
	v_fma_f32 v97, v97, v239, v239
	v_rcp_f32_e32 v100, v97
	v_exp_f32_e32 v97, v101
	v_pk_mul_f32 v[88:89], v[88:89], v[102:103]
	v_fma_f32 v97, v97, v239, v239
	v_rcp_f32_e32 v101, v97
	v_cvt_pk_bf16_f32 v88, v88, v89
	s_nop 0
	v_pk_mul_f32 v[90:91], v[90:91], v[100:101]
	s_nop 0
	v_cvt_pk_bf16_f32 v89, v90, v91
	v_pk_mul_f32 v[92:93], v[84:85], v[96:97] op_sel_hi:[1,0]
	v_pk_mul_f32 v[90:91], v[86:87], v[96:97] op_sel_hi:[1,0]
	v_exp_f32_e32 v92, v92
	v_exp_f32_e32 v93, v93
	v_exp_f32_e32 v90, v90
	v_exp_f32_e32 v91, v91
	v_fma_f32 v92, v92, v239, v239
	v_fma_f32 v93, v93, v239, v239
	v_rcp_f32_e32 v92, v92
	v_rcp_f32_e32 v93, v93
	v_fma_f32 v90, v90, v239, v239
	v_fma_f32 v91, v91, v239, v239
	v_rcp_f32_e32 v90, v90
	v_rcp_f32_e32 v91, v91
	s_nop 0
	v_pk_mul_f32 v[80:81], v[80:81], v[92:93]
	s_nop 0
	v_pk_mul_f32 v[82:83], v[82:83], v[90:91]
	v_cvt_pk_bf16_f32 v90, v80, v81
	v_mul_u32_u24_e32 v80, 0x1600, v148
	v_cvt_pk_bf16_f32 v91, v82, v83
	v_add_u32_e32 v80, v80, v114
	global_store_dwordx4 v80, v[88:91], s[0:1]
	v_fmamk_f32 v239, v234, 0x3a800000, v194
	s_nop 0
	v_rsq_f32_e32 v80, v239
	s_nop 0
	v_mov_b32_e32 v81, v80
	v_mul_f32_e32 v80, 0xbfb8aa3b, v81
	v_pk_mul_f32 v[86:87], v[76:77], v[80:81] op_sel_hi:[1,0]
	s_nop 0
	v_pk_mul_f32 v[84:85], v[78:79], v[80:81] op_sel_hi:[1,0]
	v_exp_f32_e32 v81, v86
	s_nop 0
	v_fma_f32 v81, v81, v239, v239
	v_rcp_f32_e32 v86, v81
	v_exp_f32_e32 v81, v87
	s_nop 0
	v_fma_f32 v81, v81, v239, v239
	v_rcp_f32_e32 v87, v81
	v_exp_f32_e32 v81, v84
	s_nop 0
	v_fma_f32 v81, v81, v239, v239
	v_rcp_f32_e32 v84, v81
	v_exp_f32_e32 v81, v85
	v_pk_mul_f32 v[72:73], v[72:73], v[86:87]
	v_fma_f32 v81, v81, v239, v239
	v_rcp_f32_e32 v85, v81
	v_cvt_pk_bf16_f32 v72, v72, v73
	s_nop 0
	v_pk_mul_f32 v[74:75], v[74:75], v[84:85]
	s_nop 0
	v_cvt_pk_bf16_f32 v73, v74, v75
	v_pk_mul_f32 v[76:77], v[68:69], v[80:81] op_sel_hi:[1,0]
	v_pk_mul_f32 v[74:75], v[70:71], v[80:81] op_sel_hi:[1,0]
	v_exp_f32_e32 v76, v76
	v_exp_f32_e32 v77, v77
	v_exp_f32_e32 v74, v74
	v_exp_f32_e32 v75, v75
	v_fma_f32 v76, v76, v239, v239
	v_fma_f32 v77, v77, v239, v239
	v_rcp_f32_e32 v76, v76
	v_rcp_f32_e32 v77, v77
	v_fma_f32 v74, v74, v239, v239
	v_fma_f32 v75, v75, v239, v239
	v_rcp_f32_e32 v74, v74
	v_rcp_f32_e32 v75, v75
	s_nop 0
	v_pk_mul_f32 v[64:65], v[64:65], v[76:77]
	v_add_u32_e32 v69, 0x90, v138
	s_nop 0
	v_pk_mul_f32 v[66:67], v[66:67], v[74:75]
	v_cvt_pk_bf16_f32 v74, v64, v65
	v_mul_u32_u24_e32 v64, 0x1600, v139
	v_cvt_pk_bf16_f32 v75, v66, v67
	v_add_u32_e32 v64, v64, v114
	global_store_dwordx4 v64, v[72:75], s[0:1]
	v_add_u32_e32 v67, 0x80, v138
	v_add_u32_e32 v66, 0xa0, v138
	v_add_u32_e32 v64, 0xb0, v138
	v_fmamk_f32 v239, v235, 0x3a800000, v194
	s_nop 0
	v_rsq_f32_e32 v68, v239
	s_nop 0
	v_mov_b32_e32 v70, v68
	v_mul_f32_e32 v68, 0xbfb8aa3b, v70
	v_pk_mul_f32 v[74:75], v[60:61], v[68:69] op_sel_hi:[1,0]
	v_pk_mul_f32 v[72:73], v[62:63], v[68:69] op_sel_hi:[1,0]
	v_exp_f32_e32 v74, v74
	v_exp_f32_e32 v75, v75
	v_exp_f32_e32 v72, v72
	v_exp_f32_e32 v73, v73
	v_fma_f32 v74, v74, v239, v239
	v_fma_f32 v75, v75, v239, v239
	v_rcp_f32_e32 v74, v74
	v_rcp_f32_e32 v75, v75
	v_fma_f32 v72, v72, v239, v239
	v_fma_f32 v73, v73, v239, v239
	v_rcp_f32_e32 v72, v72
	v_rcp_f32_e32 v73, v73
	s_nop 0
	s_nop 0
	v_pk_mul_f32 v[56:57], v[56:57], v[74:75]
	s_nop 0
	v_pk_mul_f32 v[58:59], v[58:59], v[72:73]
	v_cvt_pk_bf16_f32 v56, v56, v57
	v_cvt_pk_bf16_f32 v57, v58, v59
	v_pk_mul_f32 v[60:61], v[52:53], v[68:69] op_sel_hi:[1,0]
	v_pk_mul_f32 v[58:59], v[54:55], v[68:69] op_sel_hi:[1,0]
	v_exp_f32_e32 v60, v60
	v_exp_f32_e32 v61, v61
	v_exp_f32_e32 v58, v58
	v_exp_f32_e32 v59, v59
	v_fma_f32 v60, v60, v239, v239
	v_fma_f32 v61, v61, v239, v239
	v_rcp_f32_e32 v60, v60
	v_rcp_f32_e32 v61, v61
	v_fma_f32 v58, v58, v239, v239
	v_fma_f32 v59, v59, v239, v239
	v_rcp_f32_e32 v58, v58
	v_rcp_f32_e32 v59, v59
	s_nop 0
	v_pk_mul_f32 v[48:49], v[48:49], v[60:61]
	s_nop 0
	v_pk_mul_f32 v[50:51], v[50:51], v[58:59]
	v_cvt_pk_bf16_f32 v58, v48, v49
	v_mul_u32_u24_e32 v48, 0x1600, v67
	v_cvt_pk_bf16_f32 v59, v50, v51
	v_add_u32_e32 v48, v48, v114
	global_store_dwordx4 v48, v[56:59], s[0:1]
	v_fmamk_f32 v239, v236, 0x3a800000, v194
	s_nop 0
	v_rsq_f32_e32 v48, v239
	s_nop 0
	v_mov_b32_e32 v49, v48
	v_mul_f32_e32 v48, 0xbfb8aa3b, v49
	v_pk_mul_f32 v[54:55], v[44:45], v[48:49] op_sel_hi:[1,0]
	s_nop 0
	v_pk_mul_f32 v[52:53], v[46:47], v[48:49] op_sel_hi:[1,0]
	v_exp_f32_e32 v49, v54
	s_nop 0
	v_fma_f32 v49, v49, v239, v239
	v_rcp_f32_e32 v54, v49
	v_exp_f32_e32 v49, v55
	s_nop 0
	v_fma_f32 v49, v49, v239, v239
	v_rcp_f32_e32 v55, v49
	v_exp_f32_e32 v49, v52
	s_nop 0
	v_fma_f32 v49, v49, v239, v239
	v_rcp_f32_e32 v52, v49
	v_exp_f32_e32 v49, v53
	v_pk_mul_f32 v[40:41], v[40:41], v[54:55]
	v_fma_f32 v49, v49, v239, v239
	v_rcp_f32_e32 v53, v49
	v_cvt_pk_bf16_f32 v40, v40, v41
	s_nop 0
	v_pk_mul_f32 v[42:43], v[42:43], v[52:53]
	s_nop 0
	v_cvt_pk_bf16_f32 v41, v42, v43
	v_pk_mul_f32 v[44:45], v[36:37], v[48:49] op_sel_hi:[1,0]
	v_pk_mul_f32 v[42:43], v[38:39], v[48:49] op_sel_hi:[1,0]
	v_exp_f32_e32 v44, v44
	v_exp_f32_e32 v45, v45
	v_exp_f32_e32 v42, v42
	v_exp_f32_e32 v43, v43
	v_fma_f32 v44, v44, v239, v239
	v_fma_f32 v45, v45, v239, v239
	v_rcp_f32_e32 v44, v44
	v_rcp_f32_e32 v45, v45
	v_fma_f32 v42, v42, v239, v239
	v_fma_f32 v43, v43, v239, v239
	v_rcp_f32_e32 v42, v42
	v_rcp_f32_e32 v43, v43
	s_nop 0
	v_pk_mul_f32 v[32:33], v[32:33], v[44:45]
	s_nop 0
	v_pk_mul_f32 v[34:35], v[34:35], v[42:43]
	v_cvt_pk_bf16_f32 v42, v32, v33
	v_mul_u32_u24_e32 v32, 0x1600, v69
	v_cvt_pk_bf16_f32 v43, v34, v35
	v_add_u32_e32 v32, v32, v114
	global_store_dwordx4 v32, v[40:43], s[0:1]
	v_fmamk_f32 v239, v237, 0x3a800000, v194
	s_nop 0
	v_rsq_f32_e32 v32, v239
	s_nop 0
	v_mov_b32_e32 v33, v32
	v_mul_f32_e32 v32, 0xbfb8aa3b, v33
	v_pk_mul_f32 v[38:39], v[28:29], v[32:33] op_sel_hi:[1,0]
	s_nop 0
	v_pk_mul_f32 v[36:37], v[30:31], v[32:33] op_sel_hi:[1,0]
	v_exp_f32_e32 v33, v38
	s_nop 0
	v_fma_f32 v33, v33, v239, v239
	v_rcp_f32_e32 v38, v33
	v_exp_f32_e32 v33, v39
	s_nop 0
	v_fma_f32 v33, v33, v239, v239
	v_rcp_f32_e32 v39, v33
	v_exp_f32_e32 v33, v36
	s_nop 0
	v_fma_f32 v33, v33, v239, v239
	v_rcp_f32_e32 v36, v33
	v_exp_f32_e32 v33, v37
	v_pk_mul_f32 v[24:25], v[24:25], v[38:39]
	v_fma_f32 v33, v33, v239, v239
	v_rcp_f32_e32 v37, v33
	v_cvt_pk_bf16_f32 v24, v24, v25
	s_nop 0
	v_pk_mul_f32 v[26:27], v[26:27], v[36:37]
	s_nop 0
	v_cvt_pk_bf16_f32 v25, v26, v27
	v_pk_mul_f32 v[28:29], v[20:21], v[32:33] op_sel_hi:[1,0]
	v_pk_mul_f32 v[26:27], v[22:23], v[32:33] op_sel_hi:[1,0]
	v_exp_f32_e32 v28, v28
	v_exp_f32_e32 v29, v29
	v_exp_f32_e32 v26, v26
	v_exp_f32_e32 v27, v27
	v_fma_f32 v28, v28, v239, v239
	v_fma_f32 v29, v29, v239, v239
	v_rcp_f32_e32 v28, v28
	v_rcp_f32_e32 v29, v29
	v_fma_f32 v26, v26, v239, v239
	v_fma_f32 v27, v27, v239, v239
	v_rcp_f32_e32 v26, v26
	v_rcp_f32_e32 v27, v27
	s_nop 0
	v_pk_mul_f32 v[16:17], v[16:17], v[28:29]
	s_nop 0
	v_pk_mul_f32 v[18:19], v[18:19], v[26:27]
	v_cvt_pk_bf16_f32 v26, v16, v17
	v_mul_u32_u24_e32 v16, 0x1600, v66
	v_cvt_pk_bf16_f32 v27, v18, v19
	v_add_u32_e32 v16, v16, v114
	global_store_dwordx4 v16, v[24:27], s[0:1]
	v_fmamk_f32 v239, v238, 0x3a800000, v194
	s_nop 0
	v_rsq_f32_e32 v16, v239
	s_nop 0
	v_mov_b32_e32 v17, v16
	v_mul_f32_e32 v16, 0xbfb8aa3b, v17
	v_pk_mul_f32 v[22:23], v[12:13], v[16:17] op_sel_hi:[1,0]
	s_nop 0
	v_pk_mul_f32 v[20:21], v[14:15], v[16:17] op_sel_hi:[1,0]
	v_exp_f32_e32 v17, v22
	s_and_b64 vcc, exec, s[4:5]
	v_fma_f32 v17, v17, v239, v239
	v_rcp_f32_e32 v22, v17
	v_exp_f32_e32 v17, v23
	s_nop 0
	v_fma_f32 v17, v17, v239, v239
	v_rcp_f32_e32 v23, v17
	v_exp_f32_e32 v17, v20
	s_nop 0
	v_fma_f32 v17, v17, v239, v239
	v_rcp_f32_e32 v20, v17
	v_exp_f32_e32 v17, v21
	v_pk_mul_f32 v[8:9], v[8:9], v[22:23]
	v_fma_f32 v17, v17, v239, v239
	v_rcp_f32_e32 v21, v17
	v_cvt_pk_bf16_f32 v8, v8, v9
	s_nop 0
	v_pk_mul_f32 v[10:11], v[10:11], v[20:21]
	s_nop 0
	v_cvt_pk_bf16_f32 v9, v10, v11
	v_pk_mul_f32 v[12:13], v[4:5], v[16:17] op_sel_hi:[1,0]
	v_pk_mul_f32 v[10:11], v[6:7], v[16:17] op_sel_hi:[1,0]
	v_exp_f32_e32 v12, v12
	v_exp_f32_e32 v13, v13
	v_exp_f32_e32 v10, v10
	v_exp_f32_e32 v11, v11
	v_fma_f32 v12, v12, v239, v239
	v_fma_f32 v13, v13, v239, v239
	v_rcp_f32_e32 v12, v12
	v_rcp_f32_e32 v13, v13
	v_fma_f32 v10, v10, v239, v239
	v_fma_f32 v11, v11, v239, v239
	v_rcp_f32_e32 v10, v10
	v_rcp_f32_e32 v11, v11
	s_nop 0
	v_pk_mul_f32 v[0:1], v[0:1], v[12:13]
	s_nop 0
	v_pk_mul_f32 v[2:3], v[2:3], v[10:11]
	v_cvt_pk_bf16_f32 v10, v0, v1
	v_mul_u32_u24_e32 v0, 0x1600, v64
	v_cvt_pk_bf16_f32 v11, v2, v3
	v_add_u32_e32 v0, v0, v114
	global_store_dwordx4 v0, v[8:11], s[0:1]
	s_mov_b32 s0, s10
	s_cbranch_vccz .LBB0_399
	s_waitcnt vmcnt(0)
	s_cmpk_gt_u32 s25, 0xff
	s_cbranch_scc1 .LBB0_406
	s_barrier

.LBB0_2804:
	s_add_u32 s20, s18, 0xfffc0080
	s_addc_u32 s21, s19, -1
	s_add_i32 s42, 0, 0x10000
	ds_read_b128 v[138:141], v202
	ds_read_b128 v[142:145], v202 offset:1024
	ds_read_b128 v[146:149], v202 offset:2048
	ds_read_b128 v[154:157], v202 offset:3072
	s_cmp_eq_u32 s41, 12
	s_cselect_b32 s23, s9, s21
	s_cselect_b32 s22, s33, s20
	s_cselect_b32 s21, s11, s40
	s_cselect_b32 s20, s38, s39
	s_add_i32 m0, s17, 0xc000
	ds_read_b128 v[158:161], v152
	ds_read_b128 v[162:165], v152 offset:1024
	ds_read_b128 v[166:169], v152 offset:2048
	ds_read_b128 v[170:173], v152 offset:3072
	ds_read_b128 v[174:177], v152 offset:4096
	ds_read_b128 v[178:181], v152 offset:5120
	ds_read_b128 v[182:185], v152 offset:6144
	ds_read_b128 v[186:189], v152 offset:7168
	global_load_lds_dwordx4 v136, s[18:19]
	s_add_i32 m0, s17, 0xe000
	s_nop 0
	global_load_lds_dwordx4 v134, s[18:19]
	s_waitcnt lgkmcnt(8)
	s_barrier
	s_waitcnt lgkmcnt(0)
	v_mfma_f32_16x16x32_bf16 v[124:127], v[138:141], v[158:161], v[124:127]
	v_mfma_f32_16x16x32_bf16 v[116:119], v[146:149], v[158:161], v[116:119]
	v_mfma_f32_16x16x32_bf16 v[108:111], v[138:141], v[166:169], v[108:111]
	v_mfma_f32_16x16x32_bf16 v[100:103], v[146:149], v[166:169], v[100:103]
	v_mfma_f32_16x16x32_bf16 v[92:95], v[138:141], v[174:177], v[92:95]
	v_mfma_f32_16x16x32_bf16 v[84:87], v[146:149], v[174:177], v[84:87]
	v_mfma_f32_16x16x32_bf16 v[76:79], v[138:141], v[182:185], v[76:79]
	v_mfma_f32_16x16x32_bf16 v[68:71], v[146:149], v[182:185], v[68:71]
	v_mfma_f32_16x16x32_bf16 v[124:127], v[142:145], v[162:165], v[124:127]
	v_mfma_f32_16x16x32_bf16 v[116:119], v[154:157], v[162:165], v[116:119]
	v_mfma_f32_16x16x32_bf16 v[108:111], v[142:145], v[170:173], v[108:111]
	v_mfma_f32_16x16x32_bf16 v[100:103], v[154:157], v[170:173], v[100:103]
	v_mfma_f32_16x16x32_bf16 v[92:95], v[142:145], v[178:181], v[92:95]
	v_mfma_f32_16x16x32_bf16 v[84:87], v[154:157], v[178:181], v[84:87]
	v_mfma_f32_16x16x32_bf16 v[76:79], v[142:145], v[186:189], v[76:79]
	v_mfma_f32_16x16x32_bf16 v[68:71], v[154:157], v[186:189], v[68:71]
	s_barrier
	s_add_i32 s44, 0, 0x14000
	s_add_i32 s42, s42, s28
	s_mov_b32 m0, s42
	ds_read_b128 v[198:201], v203
	ds_read_b128 v[206:209], v203 offset:1024
	ds_read_b128 v[210:213], v203 offset:2048
	ds_read_b128 v[214:217], v203 offset:3072
	global_load_lds_dwordx4 v192, s[20:21]
	s_add_i32 m0, s42, 0x2000
	s_nop 0
	global_load_lds_dwordx4 v128, s[20:21]
	s_barrier
	s_waitcnt lgkmcnt(0)
	v_mfma_f32_16x16x32_bf16 v[120:123], v[198:201], v[158:161], v[120:123]
	v_mfma_f32_16x16x32_bf16 v[112:115], v[210:213], v[158:161], v[112:115]
	v_mfma_f32_16x16x32_bf16 v[104:107], v[198:201], v[166:169], v[104:107]
	v_mfma_f32_16x16x32_bf16 v[96:99], v[210:213], v[166:169], v[96:99]
	v_mfma_f32_16x16x32_bf16 v[88:91], v[198:201], v[174:177], v[88:91]
	v_mfma_f32_16x16x32_bf16 v[80:83], v[210:213], v[174:177], v[80:83]
	v_mfma_f32_16x16x32_bf16 v[72:75], v[198:201], v[182:185], v[72:75]
	v_mfma_f32_16x16x32_bf16 v[64:67], v[210:213], v[182:185], v[64:67]
	v_mfma_f32_16x16x32_bf16 v[120:123], v[206:209], v[162:165], v[120:123]
	v_mfma_f32_16x16x32_bf16 v[112:115], v[214:217], v[162:165], v[112:115]
	v_mfma_f32_16x16x32_bf16 v[104:107], v[206:209], v[170:173], v[104:107]
	v_mfma_f32_16x16x32_bf16 v[96:99], v[214:217], v[170:173], v[96:99]
	v_mfma_f32_16x16x32_bf16 v[88:91], v[206:209], v[178:181], v[88:91]
	v_mfma_f32_16x16x32_bf16 v[80:83], v[214:217], v[178:181], v[80:83]
	v_mfma_f32_16x16x32_bf16 v[72:75], v[206:209], v[186:189], v[72:75]
	v_mfma_f32_16x16x32_bf16 v[64:67], v[214:217], v[186:189], v[64:67]
	s_mov_b32 m0, s17
	s_add_u32 vcc_lo, s22, 0x80
	s_addc_u32 vcc_hi, s23, 0
	s_barrier
	ds_read_b128 v[158:161], v152 offset:16384
	ds_read_b128 v[162:165], v152 offset:17408
	ds_read_b128 v[166:169], v152 offset:18432
	ds_read_b128 v[170:173], v152 offset:19456
	ds_read_b128 v[174:177], v152 offset:20480
	ds_read_b128 v[178:181], v152 offset:21504
	ds_read_b128 v[182:185], v152 offset:22528
	ds_read_b128 v[186:189], v152 offset:23552
	global_load_lds_dwordx4 v132, s[22:23]
	s_mov_b32 m0, s29
	s_nop 0
	global_load_lds_dwordx4 v130, s[22:23]
	s_barrier
	s_waitcnt lgkmcnt(0)
	v_mfma_f32_16x16x32_bf16 v[60:63], v[138:141], v[158:161], v[60:63]
	v_mfma_f32_16x16x32_bf16 v[52:55], v[146:149], v[158:161], v[52:55]
	v_mfma_f32_16x16x32_bf16 v[44:47], v[138:141], v[166:169], v[44:47]
	v_mfma_f32_16x16x32_bf16 v[36:39], v[146:149], v[166:169], v[36:39]
	v_mfma_f32_16x16x32_bf16 v[28:31], v[138:141], v[174:177], v[28:31]
	v_mfma_f32_16x16x32_bf16 v[20:23], v[146:149], v[174:177], v[20:23]
	v_mfma_f32_16x16x32_bf16 v[12:15], v[138:141], v[182:185], v[12:15]
	v_mfma_f32_16x16x32_bf16 v[4:7], v[146:149], v[182:185], v[4:7]
	v_mfma_f32_16x16x32_bf16 v[60:63], v[142:145], v[162:165], v[60:63]
	v_mfma_f32_16x16x32_bf16 v[52:55], v[154:157], v[162:165], v[52:55]
	v_mfma_f32_16x16x32_bf16 v[44:47], v[142:145], v[170:173], v[44:47]
	v_mfma_f32_16x16x32_bf16 v[36:39], v[154:157], v[170:173], v[36:39]
	v_mfma_f32_16x16x32_bf16 v[28:31], v[142:145], v[178:181], v[28:31]
	v_mfma_f32_16x16x32_bf16 v[20:23], v[154:157], v[178:181], v[20:23]
	v_mfma_f32_16x16x32_bf16 v[12:15], v[142:145], v[186:189], v[12:15]
	v_mfma_f32_16x16x32_bf16 v[4:7], v[154:157], v[186:189], v[4:7]
	s_barrier
	s_add_u32 s42, s20, 0x40000
	s_addc_u32 s43, s21, 0
	s_add_i32 s44, s44, s28
	s_mov_b32 m0, s44
	s_nop 0
	global_load_lds_dwordx4 v192, s[42:43]
	s_add_i32 m0, s44, 0x2000
	s_nop 0
	global_load_lds_dwordx4 v128, s[42:43]
	s_waitcnt vmcnt(6)
	s_barrier
	v_mfma_f32_16x16x32_bf16 v[56:59], v[198:201], v[158:161], v[56:59]
	v_mfma_f32_16x16x32_bf16 v[48:51], v[210:213], v[158:161], v[48:51]
	v_mfma_f32_16x16x32_bf16 v[40:43], v[198:201], v[166:169], v[40:43]
	v_mfma_f32_16x16x32_bf16 v[32:35], v[210:213], v[166:169], v[32:35]
	v_mfma_f32_16x16x32_bf16 v[24:27], v[198:201], v[174:177], v[24:27]
	v_mfma_f32_16x16x32_bf16 v[16:19], v[210:213], v[174:177], v[16:19]
	v_mfma_f32_16x16x32_bf16 v[8:11], v[198:201], v[182:185], v[8:11]
	v_mfma_f32_16x16x32_bf16 v[0:3], v[210:213], v[182:185], v[0:3]
	v_mfma_f32_16x16x32_bf16 v[56:59], v[206:209], v[162:165], v[56:59]
	v_mfma_f32_16x16x32_bf16 v[48:51], v[214:217], v[162:165], v[48:51]
	v_mfma_f32_16x16x32_bf16 v[40:43], v[206:209], v[170:173], v[40:43]
	v_mfma_f32_16x16x32_bf16 v[32:35], v[214:217], v[170:173], v[32:35]
	v_mfma_f32_16x16x32_bf16 v[24:27], v[206:209], v[178:181], v[24:27]
	v_mfma_f32_16x16x32_bf16 v[16:19], v[214:217], v[178:181], v[16:19]
	v_mfma_f32_16x16x32_bf16 v[8:11], v[206:209], v[186:189], v[8:11]
	v_mfma_f32_16x16x32_bf16 v[0:3], v[214:217], v[186:189], v[0:3]
	s_add_i32 s42, 0, 0x18000
	s_barrier
	ds_read_b128 v[138:141], v204
	ds_read_b128 v[142:145], v204 offset:1024
	ds_read_b128 v[146:149], v204 offset:2048
	ds_read_b128 v[154:157], v204 offset:3072
	s_add_u32 s22, s22, 0x40000
	s_addc_u32 s23, s23, 0
	s_mov_b32 m0, s30
	ds_read_b128 v[158:161], v152 offset:32768
	ds_read_b128 v[162:165], v152 offset:33792
	ds_read_b128 v[166:169], v152 offset:34816
	ds_read_b128 v[170:173], v152 offset:35840
	ds_read_b128 v[174:177], v152 offset:36864
	ds_read_b128 v[178:181], v152 offset:37888
	ds_read_b128 v[182:185], v152 offset:38912
	ds_read_b128 v[186:189], v152 offset:39936
	global_load_lds_dwordx4 v132, s[22:23]
	s_mov_b32 m0, s31
	s_nop 0
	global_load_lds_dwordx4 v130, s[22:23]
	s_waitcnt lgkmcnt(8)
	s_barrier
	s_waitcnt lgkmcnt(0)
	v_mfma_f32_16x16x32_bf16 v[124:127], v[138:141], v[158:161], v[124:127]
	v_mfma_f32_16x16x32_bf16 v[116:119], v[146:149], v[158:161], v[116:119]
	v_mfma_f32_16x16x32_bf16 v[108:111], v[138:141], v[166:169], v[108:111]
	v_mfma_f32_16x16x32_bf16 v[100:103], v[146:149], v[166:169], v[100:103]
	v_mfma_f32_16x16x32_bf16 v[92:95], v[138:141], v[174:177], v[92:95]
	v_mfma_f32_16x16x32_bf16 v[84:87], v[146:149], v[174:177], v[84:87]
	v_mfma_f32_16x16x32_bf16 v[76:79], v[138:141], v[182:185], v[76:79]
	v_mfma_f32_16x16x32_bf16 v[68:71], v[146:149], v[182:185], v[68:71]
	v_mfma_f32_16x16x32_bf16 v[124:127], v[142:145], v[162:165], v[124:127]
	v_mfma_f32_16x16x32_bf16 v[116:119], v[154:157], v[162:165], v[116:119]
	v_mfma_f32_16x16x32_bf16 v[108:111], v[142:145], v[170:173], v[108:111]
	v_mfma_f32_16x16x32_bf16 v[100:103], v[154:157], v[170:173], v[100:103]
	v_mfma_f32_16x16x32_bf16 v[92:95], v[142:145], v[178:181], v[92:95]
	v_mfma_f32_16x16x32_bf16 v[84:87], v[154:157], v[178:181], v[84:87]
	v_mfma_f32_16x16x32_bf16 v[76:79], v[142:145], v[186:189], v[76:79]
	v_mfma_f32_16x16x32_bf16 v[68:71], v[154:157], v[186:189], v[68:71]
	s_barrier
	s_add_i32 s22, 0, 0x1c000
	s_add_i32 s23, s42, s28
	s_add_u32 s100, s20, 0x80
	s_addc_u32 s101, s21, 0
	s_mov_b32 m0, s23
	ds_read_b128 v[198:201], v205
	ds_read_b128 v[206:209], v205 offset:1024
	ds_read_b128 v[210:213], v205 offset:2048
	ds_read_b128 v[214:217], v205 offset:3072
	global_load_lds_dwordx4 v192, s[100:101]
	s_add_i32 m0, s23, 0x2000
	s_nop 0
	global_load_lds_dwordx4 v128, s[100:101]
	s_barrier
	s_waitcnt lgkmcnt(0)
	v_mfma_f32_16x16x32_bf16 v[120:123], v[198:201], v[158:161], v[120:123]
	v_mfma_f32_16x16x32_bf16 v[112:115], v[210:213], v[158:161], v[112:115]
	v_mfma_f32_16x16x32_bf16 v[104:107], v[198:201], v[166:169], v[104:107]
	v_mfma_f32_16x16x32_bf16 v[96:99], v[210:213], v[166:169], v[96:99]
	v_mfma_f32_16x16x32_bf16 v[88:91], v[198:201], v[174:177], v[88:91]
	v_mfma_f32_16x16x32_bf16 v[80:83], v[210:213], v[174:177], v[80:83]
	v_mfma_f32_16x16x32_bf16 v[72:75], v[198:201], v[182:185], v[72:75]
	v_mfma_f32_16x16x32_bf16 v[64:67], v[210:213], v[182:185], v[64:67]
	v_mfma_f32_16x16x32_bf16 v[120:123], v[206:209], v[162:165], v[120:123]
	v_mfma_f32_16x16x32_bf16 v[112:115], v[214:217], v[162:165], v[112:115]
	v_mfma_f32_16x16x32_bf16 v[104:107], v[206:209], v[170:173], v[104:107]
	v_mfma_f32_16x16x32_bf16 v[96:99], v[214:217], v[170:173], v[96:99]
	v_mfma_f32_16x16x32_bf16 v[88:91], v[206:209], v[178:181], v[88:91]
	v_mfma_f32_16x16x32_bf16 v[80:83], v[214:217], v[178:181], v[80:83]
	v_mfma_f32_16x16x32_bf16 v[72:75], v[206:209], v[186:189], v[72:75]
	v_mfma_f32_16x16x32_bf16 v[64:67], v[214:217], v[186:189], v[64:67]
	s_mov_b32 m0, s34
	s_barrier
	ds_read_b128 v[158:161], v152 offset:49152
	ds_read_b128 v[162:165], v152 offset:50176
	ds_read_b128 v[166:169], v152 offset:51200
	ds_read_b128 v[170:173], v152 offset:52224
	ds_read_b128 v[174:177], v152 offset:53248
	ds_read_b128 v[178:181], v152 offset:54272
	ds_read_b128 v[182:185], v152 offset:55296
	ds_read_b128 v[186:189], v152 offset:56320
	global_load_lds_dwordx4 v132, vcc
	s_mov_b32 m0, s35
	s_nop 0
	global_load_lds_dwordx4 v130, vcc
	s_barrier
	s_waitcnt lgkmcnt(0)
	v_mfma_f32_16x16x32_bf16 v[60:63], v[138:141], v[158:161], v[60:63]
	v_mfma_f32_16x16x32_bf16 v[52:55], v[146:149], v[158:161], v[52:55]
	v_mfma_f32_16x16x32_bf16 v[44:47], v[138:141], v[166:169], v[44:47]
	v_mfma_f32_16x16x32_bf16 v[36:39], v[146:149], v[166:169], v[36:39]
	v_mfma_f32_16x16x32_bf16 v[28:31], v[138:141], v[174:177], v[28:31]
	v_mfma_f32_16x16x32_bf16 v[20:23], v[146:149], v[174:177], v[20:23]
	v_mfma_f32_16x16x32_bf16 v[12:15], v[138:141], v[182:185], v[12:15]
	v_mfma_f32_16x16x32_bf16 v[4:7], v[146:149], v[182:185], v[4:7]
	v_mfma_f32_16x16x32_bf16 v[60:63], v[142:145], v[162:165], v[60:63]
	v_mfma_f32_16x16x32_bf16 v[52:55], v[154:157], v[162:165], v[52:55]
	v_mfma_f32_16x16x32_bf16 v[44:47], v[142:145], v[170:173], v[44:47]
	v_mfma_f32_16x16x32_bf16 v[36:39], v[154:157], v[170:173], v[36:39]
	v_mfma_f32_16x16x32_bf16 v[28:31], v[142:145], v[178:181], v[28:31]
	v_mfma_f32_16x16x32_bf16 v[20:23], v[154:157], v[178:181], v[20:23]
	v_mfma_f32_16x16x32_bf16 v[12:15], v[142:145], v[186:189], v[12:15]
	v_mfma_f32_16x16x32_bf16 v[4:7], v[154:157], v[186:189], v[4:7]
	s_barrier
	s_add_u32 s20, s20, 0x40080
	s_addc_u32 s21, s21, 0
	s_add_i32 s22, s22, s28
	s_mov_b32 m0, s22
	s_nop 0
	global_load_lds_dwordx4 v192, s[20:21]
	s_add_i32 m0, s22, 0x2000
	s_nop 0
	global_load_lds_dwordx4 v128, s[20:21]
	s_waitcnt vmcnt(6)
	s_barrier
	v_mfma_f32_16x16x32_bf16 v[56:59], v[198:201], v[158:161], v[56:59]
	v_mfma_f32_16x16x32_bf16 v[48:51], v[210:213], v[158:161], v[48:51]
	v_mfma_f32_16x16x32_bf16 v[40:43], v[198:201], v[166:169], v[40:43]
	v_mfma_f32_16x16x32_bf16 v[32:35], v[210:213], v[166:169], v[32:35]
	v_mfma_f32_16x16x32_bf16 v[24:27], v[198:201], v[174:177], v[24:27]
	v_mfma_f32_16x16x32_bf16 v[16:19], v[210:213], v[174:177], v[16:19]
	v_mfma_f32_16x16x32_bf16 v[8:11], v[198:201], v[182:185], v[8:11]
	v_mfma_f32_16x16x32_bf16 v[0:3], v[210:213], v[182:185], v[0:3]
	v_mfma_f32_16x16x32_bf16 v[56:59], v[206:209], v[162:165], v[56:59]
	v_mfma_f32_16x16x32_bf16 v[48:51], v[214:217], v[162:165], v[48:51]
	v_mfma_f32_16x16x32_bf16 v[40:43], v[206:209], v[170:173], v[40:43]
	v_mfma_f32_16x16x32_bf16 v[32:35], v[214:217], v[170:173], v[32:35]
	v_mfma_f32_16x16x32_bf16 v[24:27], v[206:209], v[178:181], v[24:27]
	v_mfma_f32_16x16x32_bf16 v[16:19], v[214:217], v[178:181], v[16:19]
	v_mfma_f32_16x16x32_bf16 v[8:11], v[206:209], v[186:189], v[8:11]
	v_mfma_f32_16x16x32_bf16 v[0:3], v[214:217], v[186:189], v[0:3]
	s_add_i32 s41, s41, 2
	s_add_u32 s39, s39, 0x100
	s_addc_u32 s40, s40, 0
	s_add_u32 s18, s18, 0x100
	s_addc_u32 s19, s19, 0
	s_cmp_gt_u32 s41, 13
	s_barrier
	s_cbranch_scc0 .LBB0_2804
	v_mov_b32_e32 v139, v252
	s_lshl_b32 s11, s16, 8
	v_readfirstlane_b32 s9, v139
	s_ashr_i32 s16, s9, 2
	s_andn2_b32 s16, s16, 63
	s_lshr_b32 s9, s9, 1
	s_add_i32 s16, s16, s11
	s_lshl_b32 s11, s37, 7
	s_and_b32 s9, s9, 0x60
	v_and_or_b32 v138, v139, 15, s16
	s_or_b32 s9, s9, s11
	v_lshrrev_b32_e32 v139, 1, v139
	v_and_or_b32 v148, v139, 24, s9
	v_ashrrev_i32_e32 v139, 31, v138
	v_lshl_add_u64 v[140:141], v[138:139], 2, s[6:7]
	v_or_b32_e32 v146, 16, v138
	v_ashrrev_i32_e32 v147, 31, v146
	v_lshl_add_u64 v[142:143], v[146:147], 2, s[6:7]
	v_or_b32_e32 v144, 32, v138
	v_ashrrev_i32_e32 v145, 31, v144
	v_lshl_add_u64 v[142:143], v[144:145], 2, s[6:7]
	v_or_b32_e32 v142, 48, v138
	v_ashrrev_i32_e32 v143, 31, v142
	v_lshl_add_u64 v[154:155], v[142:143], 2, s[6:7]
	v_pk_mul_f32 v[120:121], v[124:125], v[120:121]
	v_pk_mul_f32 v[122:123], v[126:127], v[122:123]
	v_pk_mul_f32 v[112:113], v[116:117], v[112:113]
	v_pk_mul_f32 v[114:115], v[118:119], v[114:115]
	v_ashrrev_i32_e32 v149, 31, v148
	s_movk_i32 s9, 0x1600
	v_pk_mul_f32 v[104:105], v[108:109], v[104:105]
	v_pk_mul_f32 v[106:107], v[110:111], v[106:107]
	v_pk_mul_f32 v[96:97], v[100:101], v[96:97]
	v_pk_mul_f32 v[98:99], v[102:103], v[98:99]
	v_pk_mul_f32 v[88:89], v[92:93], v[88:89]
	v_pk_mul_f32 v[90:91], v[94:95], v[90:91]
	v_pk_mul_f32 v[80:81], v[84:85], v[80:81]
	v_pk_mul_f32 v[82:83], v[86:87], v[82:83]
	v_pk_mul_f32 v[72:73], v[76:77], v[72:73]
	v_pk_mul_f32 v[74:75], v[78:79], v[74:75]
	v_pk_mul_f32 v[64:65], v[68:69], v[64:65]
	v_pk_mul_f32 v[66:67], v[70:71], v[66:67]
	v_pk_mul_f32 v[56:57], v[60:61], v[56:57]
	v_pk_mul_f32 v[58:59], v[62:63], v[58:59]
	v_pk_mul_f32 v[48:49], v[52:53], v[48:49]
	v_pk_mul_f32 v[50:51], v[54:55], v[50:51]
	v_pk_mul_f32 v[40:41], v[44:45], v[40:41]
	v_pk_mul_f32 v[42:43], v[46:47], v[42:43]
	v_pk_mul_f32 v[32:33], v[36:37], v[32:33]
	v_pk_mul_f32 v[34:35], v[38:39], v[34:35]
	v_pk_mul_f32 v[24:25], v[28:29], v[24:25]
	v_pk_mul_f32 v[26:27], v[30:31], v[26:27]
	v_pk_mul_f32 v[16:17], v[20:21], v[16:17]
	v_pk_mul_f32 v[18:19], v[22:23], v[18:19]
	v_pk_mul_f32 v[8:9], v[12:13], v[8:9]
	v_pk_mul_f32 v[10:11], v[14:15], v[10:11]
	v_pk_mul_f32 v[0:1], v[4:5], v[0:1]
	v_pk_mul_f32 v[2:3], v[6:7], v[2:3]
	s_mov_b32 s37, s10
	s_mov_b32 s16, s8
	s_mov_b64 s[20:21], s[12:13]
	v_fmamk_f32 v239, v231, 0x3a800000, v194
	s_nop 0
	v_rsq_f32_e32 v143, v239
	s_nop 0
	v_mul_f32_e32 v154, 0xbfb8aa3b, v143
	v_pk_mul_f32 v[158:159], v[124:125], v[154:155] op_sel_hi:[1,0]
	s_nop 0
	v_exp_f32_e32 v143, v158
	v_pk_mul_f32 v[156:157], v[126:127], v[154:155] op_sel_hi:[1,0]
	v_fma_f32 v143, v143, v239, v239
	v_rcp_f32_e32 v158, v143
	v_exp_f32_e32 v143, v159
	s_nop 0
	v_fma_f32 v143, v143, v239, v239
	v_rcp_f32_e32 v159, v143
	v_exp_f32_e32 v143, v156
	s_nop 0
	v_fma_f32 v143, v143, v239, v239
	v_rcp_f32_e32 v156, v143
	v_exp_f32_e32 v143, v157
	v_pk_mul_f32 v[120:121], v[120:121], v[158:159]
	v_fma_f32 v143, v143, v239, v239
	v_rcp_f32_e32 v157, v143
	v_cvt_pk_bf16_f32 v120, v120, v121
	s_nop 0
	v_pk_mul_f32 v[122:123], v[122:123], v[156:157]
	s_nop 0
	v_cvt_pk_bf16_f32 v121, v122, v123
	v_pk_mul_f32 v[124:125], v[116:117], v[154:155] op_sel_hi:[1,0]
	v_pk_mul_f32 v[122:123], v[118:119], v[154:155] op_sel_hi:[1,0]
	v_exp_f32_e32 v124, v124
	v_exp_f32_e32 v125, v125
	v_exp_f32_e32 v122, v122
	v_exp_f32_e32 v123, v123
	v_fma_f32 v124, v124, v239, v239
	v_fma_f32 v125, v125, v239, v239
	v_rcp_f32_e32 v124, v124
	v_rcp_f32_e32 v125, v125
	v_fma_f32 v122, v122, v239, v239
	v_fma_f32 v123, v123, v239, v239
	v_rcp_f32_e32 v122, v122
	v_rcp_f32_e32 v123, v123
	s_nop 0
	v_pk_mul_f32 v[112:113], v[112:113], v[124:125]
	s_nop 0
	v_pk_mul_f32 v[114:115], v[114:115], v[122:123]
	v_cvt_pk_bf16_f32 v122, v112, v113
	v_cvt_pk_bf16_f32 v123, v114, v115
	v_mul_u32_u24_e32 v116, 0x1600, v138
	v_lshlrev_b32_e32 v114, 1, v148
	v_add_u32_e32 v116, v116, v114
	global_store_dwordx4 v116, v[120:123], s[4:5]
	v_fmamk_f32 v239, v232, 0x3a800000, v194
	s_nop 0
	v_rsq_f32_e32 v116, v239
	s_nop 0
	v_mul_f32_e32 v118, 0xbfb8aa3b, v116
	v_pk_mul_f32 v[122:123], v[108:109], v[118:119] op_sel_hi:[1,0]
	v_pk_mul_f32 v[120:121], v[110:111], v[118:119] op_sel_hi:[1,0]
	v_exp_f32_e32 v117, v122
	s_nop 0
	v_fma_f32 v117, v117, v239, v239
	v_rcp_f32_e32 v122, v117
	v_exp_f32_e32 v117, v123
	s_nop 0
	v_fma_f32 v117, v117, v239, v239
	v_rcp_f32_e32 v123, v117
	v_exp_f32_e32 v117, v120
	s_nop 0
	v_fma_f32 v117, v117, v239, v239
	v_rcp_f32_e32 v120, v117
	v_exp_f32_e32 v117, v121
	s_nop 0
	v_fma_f32 v117, v117, v239, v239
	v_rcp_f32_e32 v121, v117
	s_nop 0
	v_pk_mul_f32 v[104:105], v[104:105], v[122:123]
	s_nop 0
	v_pk_mul_f32 v[106:107], v[106:107], v[120:121]
	v_cvt_pk_bf16_f32 v104, v104, v105
	v_cvt_pk_bf16_f32 v105, v106, v107
	v_pk_mul_f32 v[108:109], v[100:101], v[118:119] op_sel_hi:[1,0]
	v_pk_mul_f32 v[106:107], v[102:103], v[118:119] op_sel_hi:[1,0]
	v_exp_f32_e32 v108, v108
	v_exp_f32_e32 v109, v109
	v_exp_f32_e32 v106, v106
	v_exp_f32_e32 v107, v107
	v_fma_f32 v108, v108, v239, v239
	v_fma_f32 v109, v109, v239, v239
	v_rcp_f32_e32 v108, v108
	v_rcp_f32_e32 v109, v109
	v_fma_f32 v106, v106, v239, v239
	v_fma_f32 v107, v107, v239, v239
	v_rcp_f32_e32 v106, v106
	v_rcp_f32_e32 v107, v107
	s_nop 0
	v_pk_mul_f32 v[96:97], v[96:97], v[108:109]
	s_nop 0
	v_pk_mul_f32 v[98:99], v[98:99], v[106:107]
	v_cvt_pk_bf16_f32 v106, v96, v97
	v_mul_u32_u24_e32 v96, 0x1600, v146
	v_cvt_pk_bf16_f32 v107, v98, v99
	v_add_u32_e32 v96, v96, v114
	global_store_dwordx4 v96, v[104:107], s[4:5]
	v_fmamk_f32 v239, v233, 0x3a800000, v194
	s_nop 0
	v_rsq_f32_e32 v96, v239
	s_nop 0
	v_mov_b32_e32 v97, v96
	v_mul_f32_e32 v96, 0xbfb8aa3b, v97
	v_pk_mul_f32 v[102:103], v[92:93], v[96:97] op_sel_hi:[1,0]
	s_nop 0
	v_pk_mul_f32 v[100:101], v[94:95], v[96:97] op_sel_hi:[1,0]
	v_exp_f32_e32 v97, v102
	s_nop 0
	v_fma_f32 v97, v97, v239, v239
	v_rcp_f32_e32 v102, v97
	v_exp_f32_e32 v97, v103
	s_nop 0
	v_fma_f32 v97, v97, v239, v239
	v_rcp_f32_e32 v103, v97
	v_exp_f32_e32 v97, v100
	s_nop 0
	v_fma_f32 v97, v97, v239, v239
	v_rcp_f32_e32 v100, v97
	v_exp_f32_e32 v97, v101
	v_pk_mul_f32 v[88:89], v[88:89], v[102:103]
	v_fma_f32 v97, v97, v239, v239
	v_rcp_f32_e32 v101, v97
	v_cvt_pk_bf16_f32 v88, v88, v89
	s_nop 0
	v_pk_mul_f32 v[90:91], v[90:91], v[100:101]
	s_nop 0
	v_cvt_pk_bf16_f32 v89, v90, v91
	v_pk_mul_f32 v[92:93], v[84:85], v[96:97] op_sel_hi:[1,0]
	v_pk_mul_f32 v[90:91], v[86:87], v[96:97] op_sel_hi:[1,0]
	v_exp_f32_e32 v92, v92
	v_exp_f32_e32 v93, v93
	v_exp_f32_e32 v90, v90
	v_exp_f32_e32 v91, v91
	v_fma_f32 v92, v92, v239, v239
	v_fma_f32 v93, v93, v239, v239
	v_rcp_f32_e32 v92, v92
	v_rcp_f32_e32 v93, v93
	v_fma_f32 v90, v90, v239, v239
	v_fma_f32 v91, v91, v239, v239
	v_rcp_f32_e32 v90, v90
	v_rcp_f32_e32 v91, v91
	s_nop 0
	v_pk_mul_f32 v[80:81], v[80:81], v[92:93]
	s_nop 0
	v_pk_mul_f32 v[82:83], v[82:83], v[90:91]
	v_cvt_pk_bf16_f32 v90, v80, v81
	v_mul_u32_u24_e32 v80, 0x1600, v144
	v_cvt_pk_bf16_f32 v91, v82, v83
	v_add_u32_e32 v80, v80, v114
	global_store_dwordx4 v80, v[88:91], s[4:5]
	v_fmamk_f32 v239, v234, 0x3a800000, v194
	s_nop 0
	v_rsq_f32_e32 v80, v239
	s_nop 0
	v_mov_b32_e32 v81, v80
	v_mul_f32_e32 v80, 0xbfb8aa3b, v81
	v_pk_mul_f32 v[86:87], v[76:77], v[80:81] op_sel_hi:[1,0]
	s_nop 0
	v_pk_mul_f32 v[84:85], v[78:79], v[80:81] op_sel_hi:[1,0]
	v_exp_f32_e32 v81, v86
	s_nop 0
	v_fma_f32 v81, v81, v239, v239
	v_rcp_f32_e32 v86, v81
	v_exp_f32_e32 v81, v87
	s_nop 0
	v_fma_f32 v81, v81, v239, v239
	v_rcp_f32_e32 v87, v81
	v_exp_f32_e32 v81, v84
	s_nop 0
	v_fma_f32 v81, v81, v239, v239
	v_rcp_f32_e32 v84, v81
	v_exp_f32_e32 v81, v85
	v_pk_mul_f32 v[72:73], v[72:73], v[86:87]
	v_fma_f32 v81, v81, v239, v239
	v_rcp_f32_e32 v85, v81
	v_cvt_pk_bf16_f32 v72, v72, v73
	s_nop 0
	v_pk_mul_f32 v[74:75], v[74:75], v[84:85]
	s_nop 0
	v_cvt_pk_bf16_f32 v73, v74, v75
	v_pk_mul_f32 v[76:77], v[68:69], v[80:81] op_sel_hi:[1,0]
	v_pk_mul_f32 v[74:75], v[70:71], v[80:81] op_sel_hi:[1,0]
	v_exp_f32_e32 v76, v76
	v_exp_f32_e32 v77, v77
	v_exp_f32_e32 v74, v74
	v_exp_f32_e32 v75, v75
	v_fma_f32 v76, v76, v239, v239
	v_fma_f32 v77, v77, v239, v239
	v_rcp_f32_e32 v76, v76
	v_rcp_f32_e32 v77, v77
	v_fma_f32 v74, v74, v239, v239
	v_fma_f32 v75, v75, v239, v239
	v_rcp_f32_e32 v74, v74
	v_rcp_f32_e32 v75, v75
	s_nop 0
	v_pk_mul_f32 v[64:65], v[64:65], v[76:77]
	v_add_u32_e32 v69, 0x90, v138
	s_nop 0
	v_pk_mul_f32 v[66:67], v[66:67], v[74:75]
	v_cvt_pk_bf16_f32 v74, v64, v65
	v_mul_u32_u24_e32 v64, 0x1600, v142
	v_cvt_pk_bf16_f32 v75, v66, v67
	v_add_u32_e32 v64, v64, v114
	global_store_dwordx4 v64, v[72:75], s[4:5]
	v_add_u32_e32 v67, 0x80, v138
	v_add_u32_e32 v66, 0xa0, v138
	v_add_u32_e32 v64, 0xb0, v138
	v_fmamk_f32 v239, v235, 0x3a800000, v194
	s_nop 0
	v_rsq_f32_e32 v68, v239
	s_nop 0
	v_mov_b32_e32 v70, v68
	v_mul_f32_e32 v68, 0xbfb8aa3b, v70
	v_pk_mul_f32 v[74:75], v[60:61], v[68:69] op_sel_hi:[1,0]
	v_pk_mul_f32 v[72:73], v[62:63], v[68:69] op_sel_hi:[1,0]
	v_exp_f32_e32 v74, v74
	v_exp_f32_e32 v75, v75
	v_exp_f32_e32 v72, v72
	v_exp_f32_e32 v73, v73
	v_fma_f32 v74, v74, v239, v239
	v_fma_f32 v75, v75, v239, v239
	v_rcp_f32_e32 v74, v74
	v_rcp_f32_e32 v75, v75
	v_fma_f32 v72, v72, v239, v239
	v_fma_f32 v73, v73, v239, v239
	v_rcp_f32_e32 v72, v72
	v_rcp_f32_e32 v73, v73
	s_nop 0
	s_nop 0
	v_pk_mul_f32 v[56:57], v[56:57], v[74:75]
	s_nop 0
	v_pk_mul_f32 v[58:59], v[58:59], v[72:73]
	v_cvt_pk_bf16_f32 v56, v56, v57
	v_cvt_pk_bf16_f32 v57, v58, v59
	v_pk_mul_f32 v[60:61], v[52:53], v[68:69] op_sel_hi:[1,0]
	v_pk_mul_f32 v[58:59], v[54:55], v[68:69] op_sel_hi:[1,0]
	v_exp_f32_e32 v60, v60
	v_exp_f32_e32 v61, v61
	v_exp_f32_e32 v58, v58
	v_exp_f32_e32 v59, v59
	v_fma_f32 v60, v60, v239, v239
	v_fma_f32 v61, v61, v239, v239
	v_rcp_f32_e32 v60, v60
	v_rcp_f32_e32 v61, v61
	v_fma_f32 v58, v58, v239, v239
	v_fma_f32 v59, v59, v239, v239
	v_rcp_f32_e32 v58, v58
	v_rcp_f32_e32 v59, v59
	s_nop 0
	v_pk_mul_f32 v[48:49], v[48:49], v[60:61]
	s_nop 0
	v_pk_mul_f32 v[50:51], v[50:51], v[58:59]
	v_cvt_pk_bf16_f32 v58, v48, v49
	v_mul_u32_u24_e32 v48, 0x1600, v67
	v_cvt_pk_bf16_f32 v59, v50, v51
	v_add_u32_e32 v48, v48, v114
	global_store_dwordx4 v48, v[56:59], s[4:5]
	v_fmamk_f32 v239, v236, 0x3a800000, v194
	s_nop 0
	v_rsq_f32_e32 v48, v239
	s_nop 0
	v_mov_b32_e32 v49, v48
	v_mul_f32_e32 v48, 0xbfb8aa3b, v49
	v_pk_mul_f32 v[54:55], v[44:45], v[48:49] op_sel_hi:[1,0]
	s_nop 0
	v_pk_mul_f32 v[52:53], v[46:47], v[48:49] op_sel_hi:[1,0]
	v_exp_f32_e32 v49, v54
	s_nop 0
	v_fma_f32 v49, v49, v239, v239
	v_rcp_f32_e32 v54, v49
	v_exp_f32_e32 v49, v55
	s_nop 0
	v_fma_f32 v49, v49, v239, v239
	v_rcp_f32_e32 v55, v49
	v_exp_f32_e32 v49, v52
	s_nop 0
	v_fma_f32 v49, v49, v239, v239
	v_rcp_f32_e32 v52, v49
	v_exp_f32_e32 v49, v53
	v_pk_mul_f32 v[40:41], v[40:41], v[54:55]
	v_fma_f32 v49, v49, v239, v239
	v_rcp_f32_e32 v53, v49
	v_cvt_pk_bf16_f32 v40, v40, v41
	s_nop 0
	v_pk_mul_f32 v[42:43], v[42:43], v[52:53]
	s_nop 0
	v_cvt_pk_bf16_f32 v41, v42, v43
	v_pk_mul_f32 v[44:45], v[36:37], v[48:49] op_sel_hi:[1,0]
	v_pk_mul_f32 v[42:43], v[38:39], v[48:49] op_sel_hi:[1,0]
	v_exp_f32_e32 v44, v44
	v_exp_f32_e32 v45, v45
	v_exp_f32_e32 v42, v42
	v_exp_f32_e32 v43, v43
	v_fma_f32 v44, v44, v239, v239
	v_fma_f32 v45, v45, v239, v239
	v_rcp_f32_e32 v44, v44
	v_rcp_f32_e32 v45, v45
	v_fma_f32 v42, v42, v239, v239
	v_fma_f32 v43, v43, v239, v239
	v_rcp_f32_e32 v42, v42
	v_rcp_f32_e32 v43, v43
	s_nop 0
	v_pk_mul_f32 v[32:33], v[32:33], v[44:45]
	s_nop 0
	v_pk_mul_f32 v[34:35], v[34:35], v[42:43]
	v_cvt_pk_bf16_f32 v42, v32, v33
	v_mul_u32_u24_e32 v32, 0x1600, v69
	v_cvt_pk_bf16_f32 v43, v34, v35
	v_add_u32_e32 v32, v32, v114
	global_store_dwordx4 v32, v[40:43], s[4:5]
	v_fmamk_f32 v239, v237, 0x3a800000, v194
	s_nop 0
	v_rsq_f32_e32 v32, v239
	s_nop 0
	v_mov_b32_e32 v33, v32
	v_mul_f32_e32 v32, 0xbfb8aa3b, v33
	v_pk_mul_f32 v[38:39], v[28:29], v[32:33] op_sel_hi:[1,0]
	s_nop 0
	v_pk_mul_f32 v[36:37], v[30:31], v[32:33] op_sel_hi:[1,0]
	v_exp_f32_e32 v33, v38
	s_nop 0
	v_fma_f32 v33, v33, v239, v239
	v_rcp_f32_e32 v38, v33
	v_exp_f32_e32 v33, v39
	s_nop 0
	v_fma_f32 v33, v33, v239, v239
	v_rcp_f32_e32 v39, v33
	v_exp_f32_e32 v33, v36
	s_nop 0
	v_fma_f32 v33, v33, v239, v239
	v_rcp_f32_e32 v36, v33
	v_exp_f32_e32 v33, v37
	v_pk_mul_f32 v[24:25], v[24:25], v[38:39]
	v_fma_f32 v33, v33, v239, v239
	v_rcp_f32_e32 v37, v33
	v_cvt_pk_bf16_f32 v24, v24, v25
	s_nop 0
	v_pk_mul_f32 v[26:27], v[26:27], v[36:37]
	s_nop 0
	v_cvt_pk_bf16_f32 v25, v26, v27
	v_pk_mul_f32 v[28:29], v[20:21], v[32:33] op_sel_hi:[1,0]
	v_pk_mul_f32 v[26:27], v[22:23], v[32:33] op_sel_hi:[1,0]
	v_exp_f32_e32 v28, v28
	v_exp_f32_e32 v29, v29
	v_exp_f32_e32 v26, v26
	v_exp_f32_e32 v27, v27
	v_fma_f32 v28, v28, v239, v239
	v_fma_f32 v29, v29, v239, v239
	v_rcp_f32_e32 v28, v28
	v_rcp_f32_e32 v29, v29
	v_fma_f32 v26, v26, v239, v239
	v_fma_f32 v27, v27, v239, v239
	v_rcp_f32_e32 v26, v26
	v_rcp_f32_e32 v27, v27
	s_nop 0
	v_pk_mul_f32 v[16:17], v[16:17], v[28:29]
	s_nop 0
	v_pk_mul_f32 v[18:19], v[18:19], v[26:27]
	v_cvt_pk_bf16_f32 v26, v16, v17
	v_mul_u32_u24_e32 v16, 0x1600, v66
	v_cvt_pk_bf16_f32 v27, v18, v19
	v_add_u32_e32 v16, v16, v114
	global_store_dwordx4 v16, v[24:27], s[4:5]
	v_fmamk_f32 v239, v238, 0x3a800000, v194
	s_nop 0
	v_rsq_f32_e32 v16, v239
	s_nop 0
	v_mov_b32_e32 v17, v16
	v_mul_f32_e32 v16, 0xbfb8aa3b, v17
	v_pk_mul_f32 v[22:23], v[12:13], v[16:17] op_sel_hi:[1,0]
	s_nop 0
	v_pk_mul_f32 v[20:21], v[14:15], v[16:17] op_sel_hi:[1,0]
	v_exp_f32_e32 v17, v22
	s_and_b64 vcc, exec, s[0:1]
	v_fma_f32 v17, v17, v239, v239
	v_rcp_f32_e32 v22, v17
	v_exp_f32_e32 v17, v23
	s_nop 0
	v_fma_f32 v17, v17, v239, v239
	v_rcp_f32_e32 v23, v17
	v_exp_f32_e32 v17, v20
	s_nop 0
	v_fma_f32 v17, v17, v239, v239
	v_rcp_f32_e32 v20, v17
	v_exp_f32_e32 v17, v21
	v_pk_mul_f32 v[8:9], v[8:9], v[22:23]
	v_fma_f32 v17, v17, v239, v239
	v_rcp_f32_e32 v21, v17
	v_cvt_pk_bf16_f32 v8, v8, v9
	s_nop 0
	v_pk_mul_f32 v[10:11], v[10:11], v[20:21]
	s_nop 0
	v_cvt_pk_bf16_f32 v9, v10, v11
	v_pk_mul_f32 v[12:13], v[4:5], v[16:17] op_sel_hi:[1,0]
	v_pk_mul_f32 v[10:11], v[6:7], v[16:17] op_sel_hi:[1,0]
	v_exp_f32_e32 v12, v12
	v_exp_f32_e32 v13, v13
	v_exp_f32_e32 v10, v10
	v_exp_f32_e32 v11, v11
	v_fma_f32 v12, v12, v239, v239
	v_fma_f32 v13, v13, v239, v239
	v_rcp_f32_e32 v12, v12
	v_rcp_f32_e32 v13, v13
	v_fma_f32 v10, v10, v239, v239
	v_fma_f32 v11, v11, v239, v239
	v_rcp_f32_e32 v10, v10
	v_rcp_f32_e32 v11, v11
	s_nop 0
	v_pk_mul_f32 v[0:1], v[0:1], v[12:13]
	s_nop 0
	v_pk_mul_f32 v[2:3], v[2:3], v[10:11]
	v_cvt_pk_bf16_f32 v10, v0, v1
	v_mul_u32_u24_e32 v0, 0x1600, v64
	v_cvt_pk_bf16_f32 v11, v2, v3
	v_add_u32_e32 v0, v0, v114
	s_mov_b64 s[18:19], s[14:15]
	global_store_dwordx4 v0, v[8:11], s[4:5]
	s_cbranch_vccz .LBB0_2801
	s_waitcnt vmcnt(0)
	s_cmpk_gt_u32 s25, 0xff
	s_cbranch_scc1 .LBB0_2808
	s_barrier
